# grid barrier: s_sleep 4 instead of 1 between polls of the global counter (fewer polls contending with the leaders' atomics)
# speedup vs baseline: 1.0012x; 1.0012x over previous
.Lnb_spin_top_r:
	global_load_dword v6, v12, s[6:7] sc1
	s_waitcnt vmcnt(0)
	v_cmp_le_u32_e32 vcc, v11, v6
	s_cbranch_vccnz .Lnb_done_r
	s_sleep 4
	s_add_i32 s3, s3, 1
	s_cmp_lt_u32 s3, 0x40000
	s_cbranch_scc1 .Lnb_spin_top_r

.Lnb_spin_top_m:
	global_load_dword v6, v12, s[6:7] sc1
	s_waitcnt vmcnt(0)
	v_cmp_le_u32_e32 vcc, v11, v6
	s_cbranch_vccnz .Lnb_done_m
	s_sleep 4
	s_add_i32 s2, s2, 1
	s_cmp_lt_u32 s2, 0x40000
	s_cbranch_scc1 .Lnb_spin_top_m
